# v5 + P0b transpose loop rewritten by hand: software-pipelined, two items in flight per wave (double-buffered registers)
# speedup vs baseline: 1.0055x; 1.0055x over previous
.LBB0_73:
	s_or_b64 exec, exec, s[4:5]
	s_and_b32 s0, s2, 8
	s_cmp_eq_u32 s0, 0
	s_cselect_b64 s[12:13], -1, 0
	s_cmp_lg_u32 s0, 0
	s_waitcnt lgkmcnt(0)
	s_barrier
	s_cbranch_scc0 .LBB0_103
	s_mov_b64 s[16:17], s[68:69]
	s_load_dwordx2 s[14:15], s[16:17], 0x70
	v_mov_b32_e32 v2, v0
	s_nop 0
	v_readfirstlane_b32 s0, v2
	s_ashr_i32 s38, s0, 6
	s_add_i32 s33, s38, s67
	s_cmpk_gt_i32 s33, 0x3fff
	v_and_b32_e32 v1, 63, v2
	s_cbranch_scc1 .LBB0_97
	s_waitcnt lgkmcnt(0)
	s_add_u32 s39, s14, 0x1000000
	s_addc_u32 s40, s15, 0
	s_add_u32 s41, s14, 0xa000000
	s_addc_u32 s42, s15, 0
	s_lshl_b32 s0, s38, 13
	v_lshlrev_b32_e32 v5, 2, v1
	s_add_i32 s0, s0, 0
	v_and_b32_e32 v3, 15, v2
	v_lshrrev_b32_e32 v4, 4, v1
	v_and_b32_e32 v6, 28, v5
	v_lshlrev_b32_e32 v2, 2, v3
	v_lshl_add_u32 v3, v3, 9, s0
	v_lshlrev_b32_e32 v7, 2, v4
	v_lshlrev_b32_e32 v8, 2, v6
	v_add3_u32 v77, v3, v7, v8
	v_bitop3_b32 v8, v4, v6, 4 bitop3:0x36
	v_bitop3_b32 v9, v4, v6, 8 bitop3:0x36
	v_bitop3_b32 v10, v4, v6, 12 bitop3:0x36
	v_bitop3_b32 v11, v4, v6, 16 bitop3:0x36
	v_bitop3_b32 v12, v4, v6, 20 bitop3:0x36
	v_bitop3_b32 v6, v4, v6, 24 bitop3:0x36
	s_load_dwordx4 s[8:11], s[16:17], 0x8
	s_load_dwordx2 s[18:19], s[16:17], 0x28
	v_lshlrev_b32_e32 v76, 1, v4
	v_or_b32_e32 v7, 4, v4
	v_lshl_add_u32 v78, v8, 2, v3
	v_or_b32_e32 v8, 8, v4
	v_lshl_add_u32 v79, v9, 2, v3
	v_or_b32_e32 v9, 12, v4
	v_lshl_add_u32 v80, v10, 2, v3
	v_or_b32_e32 v10, 16, v4
	v_lshl_add_u32 v81, v11, 2, v3
	v_or_b32_e32 v11, 20, v4
	v_lshl_add_u32 v82, v12, 2, v3
	v_or_b32_e32 v12, 24, v4
	v_lshl_add_u32 v83, v6, 2, v3
	v_or_b32_e32 v6, 28, v4
	v_bitop3_b32 v4, v4, v5, 28 bitop3:0x72
	v_lshrrev_b32_e32 v85, 3, v1
	v_lshl_add_u32 v84, v4, 2, v3
	v_lshlrev_b32_e32 v3, 3, v1
	v_or_b32_e32 v86, 8, v85
	v_or_b32_e32 v87, 16, v85
	v_or_b32_e32 v88, 24, v85
	v_or_b32_e32 v90, 40, v85
	v_or_b32_e32 v91, 48, v85
	v_or_b32_e32 v92, 56, v85
	v_and_b32_e32 v4, 56, v3
	v_lshrrev_b32_e32 v3, 5, v1
	v_lshrrev_b32_e32 v13, 2, v86
	v_lshrrev_b32_e32 v15, 2, v87
	v_lshrrev_b32_e32 v17, 2, v88
	v_lshrrev_b32_e32 v20, 2, v90
	v_lshrrev_b32_e32 v22, 2, v91
	v_lshrrev_b32_e32 v24, 2, v92
	v_xor_b32_e32 v3, v3, v1
	v_xor_b32_e32 v13, v13, v1
	v_xor_b32_e32 v15, v15, v1
	v_xor_b32_e32 v17, v17, v1
	v_xor_b32_e32 v20, v20, v1
	v_xor_b32_e32 v22, v22, v1
	v_xor_b32_e32 v24, v24, v1
	v_lshlrev_b32_e32 v3, 4, v3
	v_lshlrev_b32_e32 v13, 4, v13
	v_lshlrev_b32_e32 v15, 4, v15
	v_lshlrev_b32_e32 v17, 4, v17
	v_or_b32_e32 v89, 32, v85
	v_lshlrev_b32_e32 v20, 4, v20
	v_lshlrev_b32_e32 v22, 4, v22
	v_lshlrev_b32_e32 v24, 4, v24
	s_waitcnt lgkmcnt(0)
	s_cmp_lg_u64 s[8:9], 0
	v_lshl_add_u32 v5, v85, 7, s0
	v_and_b32_e32 v3, 0x70, v3
	v_lshl_add_u32 v14, v86, 7, s0
	v_and_b32_e32 v13, 0x70, v13
	v_lshl_add_u32 v16, v87, 7, s0
	v_and_b32_e32 v15, 0x70, v15
	v_lshl_add_u32 v18, v88, 7, s0
	v_and_b32_e32 v17, 0x70, v17
	v_lshl_add_u32 v19, v89, 7, s0
	v_lshl_add_u32 v21, v90, 7, s0
	v_and_b32_e32 v20, 0x70, v20
	v_lshl_add_u32 v23, v91, 7, s0
	v_and_b32_e32 v22, 0x70, v22
	v_lshl_add_u32 v25, v92, 7, s0
	v_and_b32_e32 v24, 0x70, v24
	s_cselect_b64 s[26:27], -1, 0
	s_lshl_b32 s0, s2, 9
	s_lshl_b32 s1, s38, 6
	s_mov_b32 s25, 0
	v_mov_b32_e32 v67, 0
	v_lshlrev_b32_e32 v93, 1, v7
	v_lshlrev_b32_e32 v94, 1, v8
	v_lshlrev_b32_e32 v95, 1, v9
	v_lshlrev_b32_e32 v96, 1, v10
	v_lshlrev_b32_e32 v97, 1, v11
	v_lshlrev_b32_e32 v98, 1, v12
	v_lshlrev_b32_e32 v99, 1, v6
	s_add_i32 s43, s0, s1
	s_lshl_b32 s44, s3, 9
	s_movk_i32 s45, 0x4000
	s_mov_b32 s46, 0x20000
	s_mov_b32 s47, 0x24000
	s_mov_b32 s48, 0x40000
	s_mov_b32 s49, 0x44000
	s_mov_b32 s50, 0x60000
	s_mov_b32 s51, 0x64000
	s_mov_b32 s53, 0x80000
	s_mov_b32 s54, 0x84000
	s_mov_b32 s55, 0xa0000
	s_mov_b32 s56, 0xa4000
	s_mov_b32 s57, 0xc0000
	s_mov_b32 s58, 0xc4000
	s_mov_b32 s59, 0xe0000
	s_mov_b32 s60, 0xe4000
	s_mov_b32 s61, 0x10001
	v_add_u32_e32 v100, v5, v3
	v_add_u32_e32 v101, v14, v13
	v_add_u32_e32 v102, v16, v15
	v_add_u32_e32 v103, v18, v17
	v_add_u32_e32 v104, v19, v3
	v_add_u32_e32 v105, v21, v20
	v_add_u32_e32 v106, v23, v22
	v_add_u32_e32 v107, v25, v24
	s_mov_b64 s[28:29], 0x4000
	s_mov_b32 s62, 0x8000
	v_lshlrev_b32_e32 v66, 2, v2
	v_lshlrev_b32_e32 v68, 1, v4
	s_load_dwordx2 s[24:25], s[68:69], 0x8
	s_load_dwordx2 s[26:27], s[68:69], 0x10
	s_load_dwordx2 s[28:29], s[68:69], 0x28
	s_load_dwordx2 s[30:31], s[68:69], 0x70
	s_sub_i32 s39, s33, s67
	s_lshl_b32 s39, s39, 13
	s_mov_b32 s61, 0x10001
	v_and_b32_e32 v242, 63, v0
	v_and_b32_e32 v243, 15, v242
	v_lshrrev_b32_e32 v244, 4, v242
	v_and_b32_e32 v245, 7, v242
	v_lshrrev_b32_e32 v246, 3, v242
	v_lshrrev_b32_e32 v247, 5, v242
	v_lshlrev_b32_e32 v248, 4, v243
	v_lshl_add_u32 v198, v244, 16, v248
	v_lshl_add_u32 v199, v244, 15, v248
	v_lshlrev_b32_e32 v200, 3, v244
	v_lshlrev_b32_e32 v248, 9, v243
	v_lshl_add_u32 v248, v244, 2, v248
	v_add_u32_e32 v248, s39, v248
	v_xor_b32_e32 v249, 0, v245
	v_lshl_add_u32 v164, v249, 4, v248
	v_xor_b32_e32 v249, 1, v245
	v_lshl_add_u32 v165, v249, 4, v248
	v_xor_b32_e32 v249, 2, v245
	v_lshl_add_u32 v166, v249, 4, v248
	v_xor_b32_e32 v249, 3, v245
	v_lshl_add_u32 v167, v249, 4, v248
	v_xor_b32_e32 v249, 4, v245
	v_lshl_add_u32 v168, v249, 4, v248
	v_xor_b32_e32 v249, 5, v245
	v_lshl_add_u32 v169, v249, 4, v248
	v_xor_b32_e32 v249, 6, v245
	v_lshl_add_u32 v170, v249, 4, v248
	v_xor_b32_e32 v249, 7, v245
	v_lshl_add_u32 v171, v249, 4, v248
	v_add_u32_e32 v248, 0, v246
	v_add_u32_e32 v249, 0, v247
	v_and_b32_e32 v249, 7, v249
	v_xor_b32_e32 v249, v249, v245
	v_lshlrev_b32_e32 v249, 4, v249
	v_lshl_add_u32 v249, v248, 7, v249
	v_add_u32_e32 v182, s39, v249
	v_lshlrev_b32_e32 v249, 4, v245
	v_lshl_add_u32 v190, v248, 13, v249
	v_add_u32_e32 v248, 8, v246
	v_add_u32_e32 v249, 2, v247
	v_and_b32_e32 v249, 7, v249
	v_xor_b32_e32 v249, v249, v245
	v_lshlrev_b32_e32 v249, 4, v249
	v_lshl_add_u32 v249, v248, 7, v249
	v_add_u32_e32 v183, s39, v249
	v_lshlrev_b32_e32 v249, 4, v245
	v_lshl_add_u32 v191, v248, 13, v249
	v_add_u32_e32 v248, 16, v246
	v_add_u32_e32 v249, 4, v247
	v_and_b32_e32 v249, 7, v249
	v_xor_b32_e32 v249, v249, v245
	v_lshlrev_b32_e32 v249, 4, v249
	v_lshl_add_u32 v249, v248, 7, v249
	v_add_u32_e32 v184, s39, v249
	v_lshlrev_b32_e32 v249, 4, v245
	v_lshl_add_u32 v192, v248, 13, v249
	v_add_u32_e32 v248, 24, v246
	v_add_u32_e32 v249, 6, v247
	v_and_b32_e32 v249, 7, v249
	v_xor_b32_e32 v249, v249, v245
	v_lshlrev_b32_e32 v249, 4, v249
	v_lshl_add_u32 v249, v248, 7, v249
	v_add_u32_e32 v185, s39, v249
	v_lshlrev_b32_e32 v249, 4, v245
	v_lshl_add_u32 v193, v248, 13, v249
	v_add_u32_e32 v248, 32, v246
	v_add_u32_e32 v249, 8, v247
	v_and_b32_e32 v249, 7, v249
	v_xor_b32_e32 v249, v249, v245
	v_lshlrev_b32_e32 v249, 4, v249
	v_lshl_add_u32 v249, v248, 7, v249
	v_add_u32_e32 v186, s39, v249
	v_lshlrev_b32_e32 v249, 4, v245
	v_lshl_add_u32 v194, v248, 13, v249
	v_add_u32_e32 v248, 40, v246
	v_add_u32_e32 v249, 10, v247
	v_and_b32_e32 v249, 7, v249
	v_xor_b32_e32 v249, v249, v245
	v_lshlrev_b32_e32 v249, 4, v249
	v_lshl_add_u32 v249, v248, 7, v249
	v_add_u32_e32 v187, s39, v249
	v_lshlrev_b32_e32 v249, 4, v245
	v_lshl_add_u32 v195, v248, 13, v249
	v_add_u32_e32 v248, 48, v246
	v_add_u32_e32 v249, 12, v247
	v_and_b32_e32 v249, 7, v249
	v_xor_b32_e32 v249, v249, v245
	v_lshlrev_b32_e32 v249, 4, v249
	v_lshl_add_u32 v249, v248, 7, v249
	v_add_u32_e32 v188, s39, v249
	v_lshlrev_b32_e32 v249, 4, v245
	v_lshl_add_u32 v196, v248, 13, v249
	v_add_u32_e32 v248, 56, v246
	v_add_u32_e32 v249, 14, v247
	v_and_b32_e32 v249, 7, v249
	v_xor_b32_e32 v249, v249, v245
	v_lshlrev_b32_e32 v249, 4, v249
	v_lshl_add_u32 v249, v248, 7, v249
	v_add_u32_e32 v189, s39, v249
	v_lshlrev_b32_e32 v249, 4, v245
	v_lshl_add_u32 v197, v248, 13, v249
	s_waitcnt lgkmcnt(0)
	s_mov_b32 s34, s33
	s_cmpk_gt_i32 s34, 0x3fff
	s_cbranch_scc1 .Ltpa_done
	s_cmp_ge_u32 s34, 0x2000
	s_cbranch_scc1 .Ltpa_ldw_p0
	s_lshr_b32 s53, s34, 12
	s_and_b32 s54, s34, 0xfff
	s_lshr_b32 s55, s54, 6
	s_and_b32 s54, s54, 63
	s_lshl_b32 s56, s53, 27
	s_lshl_b32 s57, s55, 21
	s_add_u32 s56, s56, s57
	s_lshl_b32 s57, s54, 8
	s_add_u32 s56, s56, s57
	s_add_u32 s56, s56, 0x4000
	s_add_u32 s48, s26, s56
	s_addc_u32 s49, s27, 0
	s_lshl_b32 s56, s53, 14
	s_lshl_b32 s57, s55, 8
	s_add_u32 s56, s56, s57
	s_add_u32 s50, s24, s56
	s_addc_u32 s51, s25, 0
	s_lshl_b32 s56, s53, 26
	s_lshl_b32 s57, s54, 19
	s_add_u32 s56, s56, s57
	s_lshl_b32 s57, s55, 7
	s_add_u32 s56, s56, s57
	s_add_u32 s56, s56, 0x3000000
	s_add_u32 s40, s30, s56
	s_addc_u32 s41, s31, 0
	s_mov_b32 s42, 1
	s_mov_b32 s43, 24
	global_load_dwordx2 v[132:133], v200, s[50:51] offset:0
	global_load_dwordx2 v[134:135], v200, s[50:51] offset:32
	global_load_dwordx2 v[136:137], v200, s[50:51] offset:64
	global_load_dwordx2 v[138:139], v200, s[50:51] offset:96
	global_load_dwordx2 v[140:141], v200, s[50:51] offset:128
	global_load_dwordx2 v[142:143], v200, s[50:51] offset:160
	global_load_dwordx2 v[144:145], v200, s[50:51] offset:192
	global_load_dwordx2 v[146:147], v200, s[50:51] offset:224
	global_load_dwordx4 v[2:5], v198, s[48:49] nt
	v_add_u32_e32 v6, 0x8000, v198
	global_load_dwordx4 v[6:9], v6, s[48:49] nt
	v_add_u32_e32 v10, 0x40000, v198
	global_load_dwordx4 v[10:13], v10, s[48:49] nt
	v_add_u32_e32 v14, 0x48000, v198
	global_load_dwordx4 v[14:17], v14, s[48:49] nt
	v_add_u32_e32 v18, 0x80000, v198
	global_load_dwordx4 v[18:21], v18, s[48:49] nt
	v_add_u32_e32 v22, 0x88000, v198
	global_load_dwordx4 v[22:25], v22, s[48:49] nt
	v_add_u32_e32 v26, 0xc0000, v198
	global_load_dwordx4 v[26:29], v26, s[48:49] nt
	v_add_u32_e32 v30, 0xc8000, v198
	global_load_dwordx4 v[30:33], v30, s[48:49] nt
	v_add_u32_e32 v34, 0x100000, v198
	global_load_dwordx4 v[34:37], v34, s[48:49] nt
	v_add_u32_e32 v38, 0x108000, v198
	global_load_dwordx4 v[38:41], v38, s[48:49] nt
	v_add_u32_e32 v42, 0x140000, v198
	global_load_dwordx4 v[42:45], v42, s[48:49] nt
	v_add_u32_e32 v46, 0x148000, v198
	global_load_dwordx4 v[46:49], v46, s[48:49] nt
	v_add_u32_e32 v50, 0x180000, v198
	global_load_dwordx4 v[50:53], v50, s[48:49] nt
	v_add_u32_e32 v54, 0x188000, v198
	global_load_dwordx4 v[54:57], v54, s[48:49] nt
	v_add_u32_e32 v58, 0x1c0000, v198
	global_load_dwordx4 v[58:61], v58, s[48:49] nt
	v_add_u32_e32 v62, 0x1c8000, v198
	global_load_dwordx4 v[62:65], v62, s[48:49] nt
	s_branch .Ltpa_ldx_p0
.Ltpa_ldw_p0:
	s_sub_u32 s53, s34, 0x2000
	s_and_b32 s54, s53, 0xfff
	s_lshr_b32 s53, s53, 12
	s_lshr_b32 s55, s54, 6
	s_and_b32 s54, s54, 63
	s_lshl_b32 s56, s53, 26
	s_lshl_b32 s57, s55, 20
	s_add_u32 s56, s56, s57
	s_lshl_b32 s57, s54, 8
	s_add_u32 s56, s56, s57
	s_add_u32 s48, s28, s56
	s_addc_u32 s49, s29, 0
	s_lshl_b32 s56, s53, 25
	s_lshl_b32 s57, s54, 19
	s_add_u32 s56, s56, s57
	s_lshl_b32 s57, s55, 7
	s_add_u32 s56, s56, s57
	s_add_u32 s56, s56, 0xa000000
	s_add_u32 s40, s30, s56
	s_addc_u32 s41, s31, 0
	s_mov_b32 s42, 0
	s_mov_b32 s43, 16
	global_load_dwordx4 v[2:5], v199, s[48:49] nt
	v_add_u32_e32 v6, 0x4000, v199
	global_load_dwordx4 v[6:9], v6, s[48:49] nt
	v_add_u32_e32 v10, 0x20000, v199
	global_load_dwordx4 v[10:13], v10, s[48:49] nt
	v_add_u32_e32 v14, 0x24000, v199
	global_load_dwordx4 v[14:17], v14, s[48:49] nt
	v_add_u32_e32 v18, 0x40000, v199
	global_load_dwordx4 v[18:21], v18, s[48:49] nt
	v_add_u32_e32 v22, 0x44000, v199
	global_load_dwordx4 v[22:25], v22, s[48:49] nt
	v_add_u32_e32 v26, 0x60000, v199
	global_load_dwordx4 v[26:29], v26, s[48:49] nt
	v_add_u32_e32 v30, 0x64000, v199
	global_load_dwordx4 v[30:33], v30, s[48:49] nt
	v_add_u32_e32 v34, 0x80000, v199
	global_load_dwordx4 v[34:37], v34, s[48:49] nt
	v_add_u32_e32 v38, 0x84000, v199
	global_load_dwordx4 v[38:41], v38, s[48:49] nt
	v_add_u32_e32 v42, 0xa0000, v199
	global_load_dwordx4 v[42:45], v42, s[48:49] nt
	v_add_u32_e32 v46, 0xa4000, v199
	global_load_dwordx4 v[46:49], v46, s[48:49] nt
	v_add_u32_e32 v50, 0xc0000, v199
	global_load_dwordx4 v[50:53], v50, s[48:49] nt
	v_add_u32_e32 v54, 0xc4000, v199
	global_load_dwordx4 v[54:57], v54, s[48:49] nt
	v_add_u32_e32 v58, 0xe0000, v199
	global_load_dwordx4 v[58:61], v58, s[48:49] nt
	v_add_u32_e32 v62, 0xe4000, v199
	global_load_dwordx4 v[62:65], v62, s[48:49] nt
.Ltpa_ldx_p0:
.Ltpa_loop:
	s_add_i32 s35, s34, s72
	s_mov_b32 s43, 0
	s_cmpk_gt_i32 s35, 0x3fff
	s_cbranch_scc1 .Ltpa_skipA
	s_cmp_ge_u32 s35, 0x2000
	s_cbranch_scc1 .Ltpa_ldw_a1
	s_lshr_b32 s53, s35, 12
	s_and_b32 s54, s35, 0xfff
	s_lshr_b32 s55, s54, 6
	s_and_b32 s54, s54, 63
	s_lshl_b32 s56, s53, 27
	s_lshl_b32 s57, s55, 21
	s_add_u32 s56, s56, s57
	s_lshl_b32 s57, s54, 8
	s_add_u32 s56, s56, s57
	s_add_u32 s56, s56, 0x4000
	s_add_u32 s48, s26, s56
	s_addc_u32 s49, s27, 0
	s_lshl_b32 s56, s53, 14
	s_lshl_b32 s57, s55, 8
	s_add_u32 s56, s56, s57
	s_add_u32 s50, s24, s56
	s_addc_u32 s51, s25, 0
	s_lshl_b32 s56, s53, 26
	s_lshl_b32 s57, s54, 19
	s_add_u32 s56, s56, s57
	s_lshl_b32 s57, s55, 7
	s_add_u32 s56, s56, s57
	s_add_u32 s56, s56, 0x3000000
	s_add_u32 s44, s30, s56
	s_addc_u32 s45, s31, 0
	s_mov_b32 s46, 1
	s_mov_b32 s43, 24
	global_load_dwordx2 v[148:149], v200, s[50:51] offset:0
	global_load_dwordx2 v[150:151], v200, s[50:51] offset:32
	global_load_dwordx2 v[152:153], v200, s[50:51] offset:64
	global_load_dwordx2 v[154:155], v200, s[50:51] offset:96
	global_load_dwordx2 v[156:157], v200, s[50:51] offset:128
	global_load_dwordx2 v[158:159], v200, s[50:51] offset:160
	global_load_dwordx2 v[160:161], v200, s[50:51] offset:192
	global_load_dwordx2 v[162:163], v200, s[50:51] offset:224
	global_load_dwordx4 v[66:69], v198, s[48:49] nt
	v_add_u32_e32 v70, 0x8000, v198
	global_load_dwordx4 v[70:73], v70, s[48:49] nt
	v_add_u32_e32 v74, 0x40000, v198
	global_load_dwordx4 v[74:77], v74, s[48:49] nt
	v_add_u32_e32 v78, 0x48000, v198
	global_load_dwordx4 v[78:81], v78, s[48:49] nt
	v_add_u32_e32 v82, 0x80000, v198
	global_load_dwordx4 v[82:85], v82, s[48:49] nt
	v_add_u32_e32 v86, 0x88000, v198
	global_load_dwordx4 v[86:89], v86, s[48:49] nt
	v_add_u32_e32 v90, 0xc0000, v198
	global_load_dwordx4 v[90:93], v90, s[48:49] nt
	v_add_u32_e32 v94, 0xc8000, v198
	global_load_dwordx4 v[94:97], v94, s[48:49] nt
	v_add_u32_e32 v98, 0x100000, v198
	global_load_dwordx4 v[98:101], v98, s[48:49] nt
	v_add_u32_e32 v102, 0x108000, v198
	global_load_dwordx4 v[102:105], v102, s[48:49] nt
	v_add_u32_e32 v106, 0x140000, v198
	global_load_dwordx4 v[106:109], v106, s[48:49] nt
	v_add_u32_e32 v110, 0x148000, v198
	global_load_dwordx4 v[110:113], v110, s[48:49] nt
	v_add_u32_e32 v114, 0x180000, v198
	global_load_dwordx4 v[114:117], v114, s[48:49] nt
	v_add_u32_e32 v118, 0x188000, v198
	global_load_dwordx4 v[118:121], v118, s[48:49] nt
	v_add_u32_e32 v122, 0x1c0000, v198
	global_load_dwordx4 v[122:125], v122, s[48:49] nt
	v_add_u32_e32 v126, 0x1c8000, v198
	global_load_dwordx4 v[126:129], v126, s[48:49] nt
	s_branch .Ltpa_ldx_a1
.Ltpa_ldw_a1:
	s_sub_u32 s53, s35, 0x2000
	s_and_b32 s54, s53, 0xfff
	s_lshr_b32 s53, s53, 12
	s_lshr_b32 s55, s54, 6
	s_and_b32 s54, s54, 63
	s_lshl_b32 s56, s53, 26
	s_lshl_b32 s57, s55, 20
	s_add_u32 s56, s56, s57
	s_lshl_b32 s57, s54, 8
	s_add_u32 s56, s56, s57
	s_add_u32 s48, s28, s56
	s_addc_u32 s49, s29, 0
	s_lshl_b32 s56, s53, 25
	s_lshl_b32 s57, s54, 19
	s_add_u32 s56, s56, s57
	s_lshl_b32 s57, s55, 7
	s_add_u32 s56, s56, s57
	s_add_u32 s56, s56, 0xa000000
	s_add_u32 s44, s30, s56
	s_addc_u32 s45, s31, 0
	s_mov_b32 s46, 0
	s_mov_b32 s43, 16
	global_load_dwordx4 v[66:69], v199, s[48:49] nt
	v_add_u32_e32 v70, 0x4000, v199
	global_load_dwordx4 v[70:73], v70, s[48:49] nt
	v_add_u32_e32 v74, 0x20000, v199
	global_load_dwordx4 v[74:77], v74, s[48:49] nt
	v_add_u32_e32 v78, 0x24000, v199
	global_load_dwordx4 v[78:81], v78, s[48:49] nt
	v_add_u32_e32 v82, 0x40000, v199
	global_load_dwordx4 v[82:85], v82, s[48:49] nt
	v_add_u32_e32 v86, 0x44000, v199
	global_load_dwordx4 v[86:89], v86, s[48:49] nt
	v_add_u32_e32 v90, 0x60000, v199
	global_load_dwordx4 v[90:93], v90, s[48:49] nt
	v_add_u32_e32 v94, 0x64000, v199
	global_load_dwordx4 v[94:97], v94, s[48:49] nt
	v_add_u32_e32 v98, 0x80000, v199
	global_load_dwordx4 v[98:101], v98, s[48:49] nt
	v_add_u32_e32 v102, 0x84000, v199
	global_load_dwordx4 v[102:105], v102, s[48:49] nt
	v_add_u32_e32 v106, 0xa0000, v199
	global_load_dwordx4 v[106:109], v106, s[48:49] nt
	v_add_u32_e32 v110, 0xa4000, v199
	global_load_dwordx4 v[110:113], v110, s[48:49] nt
	v_add_u32_e32 v114, 0xc0000, v199
	global_load_dwordx4 v[114:117], v114, s[48:49] nt
	v_add_u32_e32 v118, 0xc4000, v199
	global_load_dwordx4 v[118:121], v118, s[48:49] nt
	v_add_u32_e32 v122, 0xe0000, v199
	global_load_dwordx4 v[122:125], v122, s[48:49] nt
	v_add_u32_e32 v126, 0xe4000, v199
	global_load_dwordx4 v[126:129], v126, s[48:49] nt
.Ltpa_ldx_a1:
.Ltpa_skipA:
	s_cmp_eq_u32 s43, 24
	s_cbranch_scc1 .Ltpa_w24_a0
	s_cmp_eq_u32 s43, 16
	s_cbranch_scc1 .Ltpa_w16_a0
	s_waitcnt vmcnt(0)
	s_branch .Ltpa_wx_a0
.Ltpa_w24_a0:
	s_waitcnt vmcnt(24)
	s_branch .Ltpa_wx_a0
.Ltpa_w16_a0:
	s_waitcnt vmcnt(16)
.Ltpa_wx_a0:
	s_cmp_eq_u32 s42, 0
	s_cbranch_scc1 .Ltpa_nomul_a0
	v_mul_f32_e32 v2, v2, v132
	v_mul_f32_e32 v6, v6, v133
	v_mul_f32_e32 v3, v3, v132
	v_mul_f32_e32 v7, v7, v133
	v_mul_f32_e32 v4, v4, v132
	v_mul_f32_e32 v8, v8, v133
	v_mul_f32_e32 v5, v5, v132
	v_mul_f32_e32 v9, v9, v133
	v_mul_f32_e32 v10, v10, v134
	v_mul_f32_e32 v14, v14, v135
	v_mul_f32_e32 v11, v11, v134
	v_mul_f32_e32 v15, v15, v135
	v_mul_f32_e32 v12, v12, v134
	v_mul_f32_e32 v16, v16, v135
	v_mul_f32_e32 v13, v13, v134
	v_mul_f32_e32 v17, v17, v135
	v_mul_f32_e32 v18, v18, v136
	v_mul_f32_e32 v22, v22, v137
	v_mul_f32_e32 v19, v19, v136
	v_mul_f32_e32 v23, v23, v137
	v_mul_f32_e32 v20, v20, v136
	v_mul_f32_e32 v24, v24, v137
	v_mul_f32_e32 v21, v21, v136
	v_mul_f32_e32 v25, v25, v137
	v_mul_f32_e32 v26, v26, v138
	v_mul_f32_e32 v30, v30, v139
	v_mul_f32_e32 v27, v27, v138
	v_mul_f32_e32 v31, v31, v139
	v_mul_f32_e32 v28, v28, v138
	v_mul_f32_e32 v32, v32, v139
	v_mul_f32_e32 v29, v29, v138
	v_mul_f32_e32 v33, v33, v139
	v_mul_f32_e32 v34, v34, v140
	v_mul_f32_e32 v38, v38, v141
	v_mul_f32_e32 v35, v35, v140
	v_mul_f32_e32 v39, v39, v141
	v_mul_f32_e32 v36, v36, v140
	v_mul_f32_e32 v40, v40, v141
	v_mul_f32_e32 v37, v37, v140
	v_mul_f32_e32 v41, v41, v141
	v_mul_f32_e32 v42, v42, v142
	v_mul_f32_e32 v46, v46, v143
	v_mul_f32_e32 v43, v43, v142
	v_mul_f32_e32 v47, v47, v143
	v_mul_f32_e32 v44, v44, v142
	v_mul_f32_e32 v48, v48, v143
	v_mul_f32_e32 v45, v45, v142
	v_mul_f32_e32 v49, v49, v143
	v_mul_f32_e32 v50, v50, v144
	v_mul_f32_e32 v54, v54, v145
	v_mul_f32_e32 v51, v51, v144
	v_mul_f32_e32 v55, v55, v145
	v_mul_f32_e32 v52, v52, v144
	v_mul_f32_e32 v56, v56, v145
	v_mul_f32_e32 v53, v53, v144
	v_mul_f32_e32 v57, v57, v145
	v_mul_f32_e32 v58, v58, v146
	v_mul_f32_e32 v62, v62, v147
	v_mul_f32_e32 v59, v59, v146
	v_mul_f32_e32 v63, v63, v147
	v_mul_f32_e32 v60, v60, v146
	v_mul_f32_e32 v64, v64, v147
	v_mul_f32_e32 v61, v61, v146
	v_mul_f32_e32 v65, v65, v147
.Ltpa_nomul_a0:
	v_cvt_pk_bf16_f32 v238, v2, v6
	v_lshrrev_b32_e32 v239, 2, v238
	v_and_b32_e32 v239, 0x10001, v239
	v_add3_u32 v238, v238, v239, s61
	v_and_b32_e32 v238, 0xfffcfffc, v238
	ds_write_b32 v164, v238
	v_cvt_pk_bf16_f32 v240, v3, v7
	v_lshrrev_b32_e32 v241, 2, v240
	v_and_b32_e32 v241, 0x10001, v241
	v_add3_u32 v240, v240, v241, s61
	v_and_b32_e32 v240, 0xfffcfffc, v240
	ds_write_b32 v164, v240 offset:128
	v_cvt_pk_bf16_f32 v238, v4, v8
	v_lshrrev_b32_e32 v239, 2, v238
	v_and_b32_e32 v239, 0x10001, v239
	v_add3_u32 v238, v238, v239, s61
	v_and_b32_e32 v238, 0xfffcfffc, v238
	ds_write_b32 v164, v238 offset:256
	v_cvt_pk_bf16_f32 v240, v5, v9
	v_lshrrev_b32_e32 v241, 2, v240
	v_and_b32_e32 v241, 0x10001, v241
	v_add3_u32 v240, v240, v241, s61
	v_and_b32_e32 v240, 0xfffcfffc, v240
	ds_write_b32 v164, v240 offset:384
	v_cvt_pk_bf16_f32 v238, v10, v14
	v_lshrrev_b32_e32 v239, 2, v238
	v_and_b32_e32 v239, 0x10001, v239
	v_add3_u32 v238, v238, v239, s61
	v_and_b32_e32 v238, 0xfffcfffc, v238
	ds_write_b32 v165, v238
	v_cvt_pk_bf16_f32 v240, v11, v15
	v_lshrrev_b32_e32 v241, 2, v240
	v_and_b32_e32 v241, 0x10001, v241
	v_add3_u32 v240, v240, v241, s61
	v_and_b32_e32 v240, 0xfffcfffc, v240
	ds_write_b32 v165, v240 offset:128
	v_cvt_pk_bf16_f32 v238, v12, v16
	v_lshrrev_b32_e32 v239, 2, v238
	v_and_b32_e32 v239, 0x10001, v239
	v_add3_u32 v238, v238, v239, s61
	v_and_b32_e32 v238, 0xfffcfffc, v238
	ds_write_b32 v165, v238 offset:256
	v_cvt_pk_bf16_f32 v240, v13, v17
	v_lshrrev_b32_e32 v241, 2, v240
	v_and_b32_e32 v241, 0x10001, v241
	v_add3_u32 v240, v240, v241, s61
	v_and_b32_e32 v240, 0xfffcfffc, v240
	ds_write_b32 v165, v240 offset:384
	v_cvt_pk_bf16_f32 v238, v18, v22
	v_lshrrev_b32_e32 v239, 2, v238
	v_and_b32_e32 v239, 0x10001, v239
	v_add3_u32 v238, v238, v239, s61
	v_and_b32_e32 v238, 0xfffcfffc, v238
	ds_write_b32 v166, v238
	v_cvt_pk_bf16_f32 v240, v19, v23
	v_lshrrev_b32_e32 v241, 2, v240
	v_and_b32_e32 v241, 0x10001, v241
	v_add3_u32 v240, v240, v241, s61
	v_and_b32_e32 v240, 0xfffcfffc, v240
	ds_write_b32 v166, v240 offset:128
	v_cvt_pk_bf16_f32 v238, v20, v24
	v_lshrrev_b32_e32 v239, 2, v238
	v_and_b32_e32 v239, 0x10001, v239
	v_add3_u32 v238, v238, v239, s61
	v_and_b32_e32 v238, 0xfffcfffc, v238
	ds_write_b32 v166, v238 offset:256
	v_cvt_pk_bf16_f32 v240, v21, v25
	v_lshrrev_b32_e32 v241, 2, v240
	v_and_b32_e32 v241, 0x10001, v241
	v_add3_u32 v240, v240, v241, s61
	v_and_b32_e32 v240, 0xfffcfffc, v240
	ds_write_b32 v166, v240 offset:384
	v_cvt_pk_bf16_f32 v238, v26, v30
	v_lshrrev_b32_e32 v239, 2, v238
	v_and_b32_e32 v239, 0x10001, v239
	v_add3_u32 v238, v238, v239, s61
	v_and_b32_e32 v238, 0xfffcfffc, v238
	ds_write_b32 v167, v238
	v_cvt_pk_bf16_f32 v240, v27, v31
	v_lshrrev_b32_e32 v241, 2, v240
	v_and_b32_e32 v241, 0x10001, v241
	v_add3_u32 v240, v240, v241, s61
	v_and_b32_e32 v240, 0xfffcfffc, v240
	ds_write_b32 v167, v240 offset:128
	v_cvt_pk_bf16_f32 v238, v28, v32
	v_lshrrev_b32_e32 v239, 2, v238
	v_and_b32_e32 v239, 0x10001, v239
	v_add3_u32 v238, v238, v239, s61
	v_and_b32_e32 v238, 0xfffcfffc, v238
	ds_write_b32 v167, v238 offset:256
	v_cvt_pk_bf16_f32 v240, v29, v33
	v_lshrrev_b32_e32 v241, 2, v240
	v_and_b32_e32 v241, 0x10001, v241
	v_add3_u32 v240, v240, v241, s61
	v_and_b32_e32 v240, 0xfffcfffc, v240
	ds_write_b32 v167, v240 offset:384
	v_cvt_pk_bf16_f32 v238, v34, v38
	v_lshrrev_b32_e32 v239, 2, v238
	v_and_b32_e32 v239, 0x10001, v239
	v_add3_u32 v238, v238, v239, s61
	v_and_b32_e32 v238, 0xfffcfffc, v238
	ds_write_b32 v168, v238
	v_cvt_pk_bf16_f32 v240, v35, v39
	v_lshrrev_b32_e32 v241, 2, v240
	v_and_b32_e32 v241, 0x10001, v241
	v_add3_u32 v240, v240, v241, s61
	v_and_b32_e32 v240, 0xfffcfffc, v240
	ds_write_b32 v168, v240 offset:128
	v_cvt_pk_bf16_f32 v238, v36, v40
	v_lshrrev_b32_e32 v239, 2, v238
	v_and_b32_e32 v239, 0x10001, v239
	v_add3_u32 v238, v238, v239, s61
	v_and_b32_e32 v238, 0xfffcfffc, v238
	ds_write_b32 v168, v238 offset:256
	v_cvt_pk_bf16_f32 v240, v37, v41
	v_lshrrev_b32_e32 v241, 2, v240
	v_and_b32_e32 v241, 0x10001, v241
	v_add3_u32 v240, v240, v241, s61
	v_and_b32_e32 v240, 0xfffcfffc, v240
	ds_write_b32 v168, v240 offset:384
	v_cvt_pk_bf16_f32 v238, v42, v46
	v_lshrrev_b32_e32 v239, 2, v238
	v_and_b32_e32 v239, 0x10001, v239
	v_add3_u32 v238, v238, v239, s61
	v_and_b32_e32 v238, 0xfffcfffc, v238
	ds_write_b32 v169, v238
	v_cvt_pk_bf16_f32 v240, v43, v47
	v_lshrrev_b32_e32 v241, 2, v240
	v_and_b32_e32 v241, 0x10001, v241
	v_add3_u32 v240, v240, v241, s61
	v_and_b32_e32 v240, 0xfffcfffc, v240
	ds_write_b32 v169, v240 offset:128
	v_cvt_pk_bf16_f32 v238, v44, v48
	v_lshrrev_b32_e32 v239, 2, v238
	v_and_b32_e32 v239, 0x10001, v239
	v_add3_u32 v238, v238, v239, s61
	v_and_b32_e32 v238, 0xfffcfffc, v238
	ds_write_b32 v169, v238 offset:256
	v_cvt_pk_bf16_f32 v240, v45, v49
	v_lshrrev_b32_e32 v241, 2, v240
	v_and_b32_e32 v241, 0x10001, v241
	v_add3_u32 v240, v240, v241, s61
	v_and_b32_e32 v240, 0xfffcfffc, v240
	ds_write_b32 v169, v240 offset:384
	v_cvt_pk_bf16_f32 v238, v50, v54
	v_lshrrev_b32_e32 v239, 2, v238
	v_and_b32_e32 v239, 0x10001, v239
	v_add3_u32 v238, v238, v239, s61
	v_and_b32_e32 v238, 0xfffcfffc, v238
	ds_write_b32 v170, v238
	v_cvt_pk_bf16_f32 v240, v51, v55
	v_lshrrev_b32_e32 v241, 2, v240
	v_and_b32_e32 v241, 0x10001, v241
	v_add3_u32 v240, v240, v241, s61
	v_and_b32_e32 v240, 0xfffcfffc, v240
	ds_write_b32 v170, v240 offset:128
	v_cvt_pk_bf16_f32 v238, v52, v56
	v_lshrrev_b32_e32 v239, 2, v238
	v_and_b32_e32 v239, 0x10001, v239
	v_add3_u32 v238, v238, v239, s61
	v_and_b32_e32 v238, 0xfffcfffc, v238
	ds_write_b32 v170, v238 offset:256
	v_cvt_pk_bf16_f32 v240, v53, v57
	v_lshrrev_b32_e32 v241, 2, v240
	v_and_b32_e32 v241, 0x10001, v241
	v_add3_u32 v240, v240, v241, s61
	v_and_b32_e32 v240, 0xfffcfffc, v240
	ds_write_b32 v170, v240 offset:384
	v_cvt_pk_bf16_f32 v238, v58, v62
	v_lshrrev_b32_e32 v239, 2, v238
	v_and_b32_e32 v239, 0x10001, v239
	v_add3_u32 v238, v238, v239, s61
	v_and_b32_e32 v238, 0xfffcfffc, v238
	ds_write_b32 v171, v238
	v_cvt_pk_bf16_f32 v240, v59, v63
	v_lshrrev_b32_e32 v241, 2, v240
	v_and_b32_e32 v241, 0x10001, v241
	v_add3_u32 v240, v240, v241, s61
	v_and_b32_e32 v240, 0xfffcfffc, v240
	ds_write_b32 v171, v240 offset:128
	v_cvt_pk_bf16_f32 v238, v60, v64
	v_lshrrev_b32_e32 v239, 2, v238
	v_and_b32_e32 v239, 0x10001, v239
	v_add3_u32 v238, v238, v239, s61
	v_and_b32_e32 v238, 0xfffcfffc, v238
	ds_write_b32 v171, v238 offset:256
	v_cvt_pk_bf16_f32 v240, v61, v65
	v_lshrrev_b32_e32 v241, 2, v240
	v_and_b32_e32 v241, 0x10001, v241
	v_add3_u32 v240, v240, v241, s61
	v_and_b32_e32 v240, 0xfffcfffc, v240
	ds_write_b32 v171, v240 offset:384
	s_waitcnt lgkmcnt(0)
	ds_read_b128 v[202:205], v182
	ds_read_b128 v[206:209], v183
	ds_read_b128 v[210:213], v184
	ds_read_b128 v[214:217], v185
	s_waitcnt lgkmcnt(3)
	global_store_dwordx4 v190, v[202:205], s[40:41] nt
	s_waitcnt lgkmcnt(2)
	global_store_dwordx4 v191, v[206:209], s[40:41] nt
	s_waitcnt lgkmcnt(1)
	global_store_dwordx4 v192, v[210:213], s[40:41] nt
	s_waitcnt lgkmcnt(0)
	global_store_dwordx4 v193, v[214:217], s[40:41] nt
	ds_read_b128 v[218:221], v186
	ds_read_b128 v[222:225], v187
	ds_read_b128 v[230:233], v188
	ds_read_b128 v[234:237], v189
	s_waitcnt lgkmcnt(3)
	global_store_dwordx4 v194, v[218:221], s[40:41] nt
	s_waitcnt lgkmcnt(2)
	global_store_dwordx4 v195, v[222:225], s[40:41] nt
	s_waitcnt lgkmcnt(1)
	global_store_dwordx4 v196, v[230:233], s[40:41] nt
	s_waitcnt lgkmcnt(0)
	global_store_dwordx4 v197, v[234:237], s[40:41] nt
	s_cmpk_gt_i32 s35, 0x3fff
	s_cbranch_scc1 .Ltpa_done
	s_add_i32 s34, s35, s72
	s_mov_b32 s43, 0
	s_cmpk_gt_i32 s34, 0x3fff
	s_cbranch_scc1 .Ltpa_skipB
	s_cmp_ge_u32 s34, 0x2000
	s_cbranch_scc1 .Ltpa_ldw_b0
	s_lshr_b32 s53, s34, 12
	s_and_b32 s54, s34, 0xfff
	s_lshr_b32 s55, s54, 6
	s_and_b32 s54, s54, 63
	s_lshl_b32 s56, s53, 27
	s_lshl_b32 s57, s55, 21
	s_add_u32 s56, s56, s57
	s_lshl_b32 s57, s54, 8
	s_add_u32 s56, s56, s57
	s_add_u32 s56, s56, 0x4000
	s_add_u32 s48, s26, s56
	s_addc_u32 s49, s27, 0
	s_lshl_b32 s56, s53, 14
	s_lshl_b32 s57, s55, 8
	s_add_u32 s56, s56, s57
	s_add_u32 s50, s24, s56
	s_addc_u32 s51, s25, 0
	s_lshl_b32 s56, s53, 26
	s_lshl_b32 s57, s54, 19
	s_add_u32 s56, s56, s57
	s_lshl_b32 s57, s55, 7
	s_add_u32 s56, s56, s57
	s_add_u32 s56, s56, 0x3000000
	s_add_u32 s40, s30, s56
	s_addc_u32 s41, s31, 0
	s_mov_b32 s42, 1
	s_mov_b32 s43, 24
	global_load_dwordx2 v[132:133], v200, s[50:51] offset:0
	global_load_dwordx2 v[134:135], v200, s[50:51] offset:32
	global_load_dwordx2 v[136:137], v200, s[50:51] offset:64
	global_load_dwordx2 v[138:139], v200, s[50:51] offset:96
	global_load_dwordx2 v[140:141], v200, s[50:51] offset:128
	global_load_dwordx2 v[142:143], v200, s[50:51] offset:160
	global_load_dwordx2 v[144:145], v200, s[50:51] offset:192
	global_load_dwordx2 v[146:147], v200, s[50:51] offset:224
	global_load_dwordx4 v[2:5], v198, s[48:49] nt
	v_add_u32_e32 v6, 0x8000, v198
	global_load_dwordx4 v[6:9], v6, s[48:49] nt
	v_add_u32_e32 v10, 0x40000, v198
	global_load_dwordx4 v[10:13], v10, s[48:49] nt
	v_add_u32_e32 v14, 0x48000, v198
	global_load_dwordx4 v[14:17], v14, s[48:49] nt
	v_add_u32_e32 v18, 0x80000, v198
	global_load_dwordx4 v[18:21], v18, s[48:49] nt
	v_add_u32_e32 v22, 0x88000, v198
	global_load_dwordx4 v[22:25], v22, s[48:49] nt
	v_add_u32_e32 v26, 0xc0000, v198
	global_load_dwordx4 v[26:29], v26, s[48:49] nt
	v_add_u32_e32 v30, 0xc8000, v198
	global_load_dwordx4 v[30:33], v30, s[48:49] nt
	v_add_u32_e32 v34, 0x100000, v198
	global_load_dwordx4 v[34:37], v34, s[48:49] nt
	v_add_u32_e32 v38, 0x108000, v198
	global_load_dwordx4 v[38:41], v38, s[48:49] nt
	v_add_u32_e32 v42, 0x140000, v198
	global_load_dwordx4 v[42:45], v42, s[48:49] nt
	v_add_u32_e32 v46, 0x148000, v198
	global_load_dwordx4 v[46:49], v46, s[48:49] nt
	v_add_u32_e32 v50, 0x180000, v198
	global_load_dwordx4 v[50:53], v50, s[48:49] nt
	v_add_u32_e32 v54, 0x188000, v198
	global_load_dwordx4 v[54:57], v54, s[48:49] nt
	v_add_u32_e32 v58, 0x1c0000, v198
	global_load_dwordx4 v[58:61], v58, s[48:49] nt
	v_add_u32_e32 v62, 0x1c8000, v198
	global_load_dwordx4 v[62:65], v62, s[48:49] nt
	s_branch .Ltpa_ldx_b0

.Ltpa_wx_b1:
	s_cmp_eq_u32 s46, 0
	s_cbranch_scc1 .Ltpa_nomul_b1
	v_mul_f32_e32 v66, v66, v148
	v_mul_f32_e32 v70, v70, v149
	v_mul_f32_e32 v67, v67, v148
	v_mul_f32_e32 v71, v71, v149
	v_mul_f32_e32 v68, v68, v148
	v_mul_f32_e32 v72, v72, v149
	v_mul_f32_e32 v69, v69, v148
	v_mul_f32_e32 v73, v73, v149
	v_mul_f32_e32 v74, v74, v150
	v_mul_f32_e32 v78, v78, v151
	v_mul_f32_e32 v75, v75, v150
	v_mul_f32_e32 v79, v79, v151
	v_mul_f32_e32 v76, v76, v150
	v_mul_f32_e32 v80, v80, v151
	v_mul_f32_e32 v77, v77, v150
	v_mul_f32_e32 v81, v81, v151
	v_mul_f32_e32 v82, v82, v152
	v_mul_f32_e32 v86, v86, v153
	v_mul_f32_e32 v83, v83, v152
	v_mul_f32_e32 v87, v87, v153
	v_mul_f32_e32 v84, v84, v152
	v_mul_f32_e32 v88, v88, v153
	v_mul_f32_e32 v85, v85, v152
	v_mul_f32_e32 v89, v89, v153
	v_mul_f32_e32 v90, v90, v154
	v_mul_f32_e32 v94, v94, v155
	v_mul_f32_e32 v91, v91, v154
	v_mul_f32_e32 v95, v95, v155
	v_mul_f32_e32 v92, v92, v154
	v_mul_f32_e32 v96, v96, v155
	v_mul_f32_e32 v93, v93, v154
	v_mul_f32_e32 v97, v97, v155
	v_mul_f32_e32 v98, v98, v156
	v_mul_f32_e32 v102, v102, v157
	v_mul_f32_e32 v99, v99, v156
	v_mul_f32_e32 v103, v103, v157
	v_mul_f32_e32 v100, v100, v156
	v_mul_f32_e32 v104, v104, v157
	v_mul_f32_e32 v101, v101, v156
	v_mul_f32_e32 v105, v105, v157
	v_mul_f32_e32 v106, v106, v158
	v_mul_f32_e32 v110, v110, v159
	v_mul_f32_e32 v107, v107, v158
	v_mul_f32_e32 v111, v111, v159
	v_mul_f32_e32 v108, v108, v158
	v_mul_f32_e32 v112, v112, v159
	v_mul_f32_e32 v109, v109, v158
	v_mul_f32_e32 v113, v113, v159
	v_mul_f32_e32 v114, v114, v160
	v_mul_f32_e32 v118, v118, v161
	v_mul_f32_e32 v115, v115, v160
	v_mul_f32_e32 v119, v119, v161
	v_mul_f32_e32 v116, v116, v160
	v_mul_f32_e32 v120, v120, v161
	v_mul_f32_e32 v117, v117, v160
	v_mul_f32_e32 v121, v121, v161
	v_mul_f32_e32 v122, v122, v162
	v_mul_f32_e32 v126, v126, v163
	v_mul_f32_e32 v123, v123, v162
	v_mul_f32_e32 v127, v127, v163
	v_mul_f32_e32 v124, v124, v162
	v_mul_f32_e32 v128, v128, v163
	v_mul_f32_e32 v125, v125, v162
	v_mul_f32_e32 v129, v129, v163
.Ltpa_nomul_b1:
	v_cvt_pk_bf16_f32 v238, v66, v70
	v_lshrrev_b32_e32 v239, 2, v238
	v_and_b32_e32 v239, 0x10001, v239
	v_add3_u32 v238, v238, v239, s61
	v_and_b32_e32 v238, 0xfffcfffc, v238
	ds_write_b32 v164, v238
	v_cvt_pk_bf16_f32 v240, v67, v71
	v_lshrrev_b32_e32 v241, 2, v240
	v_and_b32_e32 v241, 0x10001, v241
	v_add3_u32 v240, v240, v241, s61
	v_and_b32_e32 v240, 0xfffcfffc, v240
	ds_write_b32 v164, v240 offset:128
	v_cvt_pk_bf16_f32 v238, v68, v72
	v_lshrrev_b32_e32 v239, 2, v238
	v_and_b32_e32 v239, 0x10001, v239
	v_add3_u32 v238, v238, v239, s61
	v_and_b32_e32 v238, 0xfffcfffc, v238
	ds_write_b32 v164, v238 offset:256
	v_cvt_pk_bf16_f32 v240, v69, v73
	v_lshrrev_b32_e32 v241, 2, v240
	v_and_b32_e32 v241, 0x10001, v241
	v_add3_u32 v240, v240, v241, s61
	v_and_b32_e32 v240, 0xfffcfffc, v240
	ds_write_b32 v164, v240 offset:384
	v_cvt_pk_bf16_f32 v238, v74, v78
	v_lshrrev_b32_e32 v239, 2, v238
	v_and_b32_e32 v239, 0x10001, v239
	v_add3_u32 v238, v238, v239, s61
	v_and_b32_e32 v238, 0xfffcfffc, v238
	ds_write_b32 v165, v238
	v_cvt_pk_bf16_f32 v240, v75, v79
	v_lshrrev_b32_e32 v241, 2, v240
	v_and_b32_e32 v241, 0x10001, v241
	v_add3_u32 v240, v240, v241, s61
	v_and_b32_e32 v240, 0xfffcfffc, v240
	ds_write_b32 v165, v240 offset:128
	v_cvt_pk_bf16_f32 v238, v76, v80
	v_lshrrev_b32_e32 v239, 2, v238
	v_and_b32_e32 v239, 0x10001, v239
	v_add3_u32 v238, v238, v239, s61
	v_and_b32_e32 v238, 0xfffcfffc, v238
	ds_write_b32 v165, v238 offset:256
	v_cvt_pk_bf16_f32 v240, v77, v81
	v_lshrrev_b32_e32 v241, 2, v240
	v_and_b32_e32 v241, 0x10001, v241
	v_add3_u32 v240, v240, v241, s61
	v_and_b32_e32 v240, 0xfffcfffc, v240
	ds_write_b32 v165, v240 offset:384
	v_cvt_pk_bf16_f32 v238, v82, v86
	v_lshrrev_b32_e32 v239, 2, v238
	v_and_b32_e32 v239, 0x10001, v239
	v_add3_u32 v238, v238, v239, s61
	v_and_b32_e32 v238, 0xfffcfffc, v238
	ds_write_b32 v166, v238
	v_cvt_pk_bf16_f32 v240, v83, v87
	v_lshrrev_b32_e32 v241, 2, v240
	v_and_b32_e32 v241, 0x10001, v241
	v_add3_u32 v240, v240, v241, s61
	v_and_b32_e32 v240, 0xfffcfffc, v240
	ds_write_b32 v166, v240 offset:128
	v_cvt_pk_bf16_f32 v238, v84, v88
	v_lshrrev_b32_e32 v239, 2, v238
	v_and_b32_e32 v239, 0x10001, v239
	v_add3_u32 v238, v238, v239, s61
	v_and_b32_e32 v238, 0xfffcfffc, v238
	ds_write_b32 v166, v238 offset:256
	v_cvt_pk_bf16_f32 v240, v85, v89
	v_lshrrev_b32_e32 v241, 2, v240
	v_and_b32_e32 v241, 0x10001, v241
	v_add3_u32 v240, v240, v241, s61
	v_and_b32_e32 v240, 0xfffcfffc, v240
	ds_write_b32 v166, v240 offset:384
	v_cvt_pk_bf16_f32 v238, v90, v94
	v_lshrrev_b32_e32 v239, 2, v238
	v_and_b32_e32 v239, 0x10001, v239
	v_add3_u32 v238, v238, v239, s61
	v_and_b32_e32 v238, 0xfffcfffc, v238
	ds_write_b32 v167, v238
	v_cvt_pk_bf16_f32 v240, v91, v95
	v_lshrrev_b32_e32 v241, 2, v240
	v_and_b32_e32 v241, 0x10001, v241
	v_add3_u32 v240, v240, v241, s61
	v_and_b32_e32 v240, 0xfffcfffc, v240
	ds_write_b32 v167, v240 offset:128
	v_cvt_pk_bf16_f32 v238, v92, v96
	v_lshrrev_b32_e32 v239, 2, v238
	v_and_b32_e32 v239, 0x10001, v239
	v_add3_u32 v238, v238, v239, s61
	v_and_b32_e32 v238, 0xfffcfffc, v238
	ds_write_b32 v167, v238 offset:256
	v_cvt_pk_bf16_f32 v240, v93, v97
	v_lshrrev_b32_e32 v241, 2, v240
	v_and_b32_e32 v241, 0x10001, v241
	v_add3_u32 v240, v240, v241, s61
	v_and_b32_e32 v240, 0xfffcfffc, v240
	ds_write_b32 v167, v240 offset:384
	v_cvt_pk_bf16_f32 v238, v98, v102
	v_lshrrev_b32_e32 v239, 2, v238
	v_and_b32_e32 v239, 0x10001, v239
	v_add3_u32 v238, v238, v239, s61
	v_and_b32_e32 v238, 0xfffcfffc, v238
	ds_write_b32 v168, v238
	v_cvt_pk_bf16_f32 v240, v99, v103
	v_lshrrev_b32_e32 v241, 2, v240
	v_and_b32_e32 v241, 0x10001, v241
	v_add3_u32 v240, v240, v241, s61
	v_and_b32_e32 v240, 0xfffcfffc, v240
	ds_write_b32 v168, v240 offset:128
	v_cvt_pk_bf16_f32 v238, v100, v104
	v_lshrrev_b32_e32 v239, 2, v238
	v_and_b32_e32 v239, 0x10001, v239
	v_add3_u32 v238, v238, v239, s61
	v_and_b32_e32 v238, 0xfffcfffc, v238
	ds_write_b32 v168, v238 offset:256
	v_cvt_pk_bf16_f32 v240, v101, v105
	v_lshrrev_b32_e32 v241, 2, v240
	v_and_b32_e32 v241, 0x10001, v241
	v_add3_u32 v240, v240, v241, s61
	v_and_b32_e32 v240, 0xfffcfffc, v240
	ds_write_b32 v168, v240 offset:384
	v_cvt_pk_bf16_f32 v238, v106, v110
	v_lshrrev_b32_e32 v239, 2, v238
	v_and_b32_e32 v239, 0x10001, v239
	v_add3_u32 v238, v238, v239, s61
	v_and_b32_e32 v238, 0xfffcfffc, v238
	ds_write_b32 v169, v238
	v_cvt_pk_bf16_f32 v240, v107, v111
	v_lshrrev_b32_e32 v241, 2, v240
	v_and_b32_e32 v241, 0x10001, v241
	v_add3_u32 v240, v240, v241, s61
	v_and_b32_e32 v240, 0xfffcfffc, v240
	ds_write_b32 v169, v240 offset:128
	v_cvt_pk_bf16_f32 v238, v108, v112
	v_lshrrev_b32_e32 v239, 2, v238
	v_and_b32_e32 v239, 0x10001, v239
	v_add3_u32 v238, v238, v239, s61
	v_and_b32_e32 v238, 0xfffcfffc, v238
	ds_write_b32 v169, v238 offset:256
	v_cvt_pk_bf16_f32 v240, v109, v113
	v_lshrrev_b32_e32 v241, 2, v240
	v_and_b32_e32 v241, 0x10001, v241
	v_add3_u32 v240, v240, v241, s61
	v_and_b32_e32 v240, 0xfffcfffc, v240
	ds_write_b32 v169, v240 offset:384
	v_cvt_pk_bf16_f32 v238, v114, v118
	v_lshrrev_b32_e32 v239, 2, v238
	v_and_b32_e32 v239, 0x10001, v239
	v_add3_u32 v238, v238, v239, s61
	v_and_b32_e32 v238, 0xfffcfffc, v238
	ds_write_b32 v170, v238
	v_cvt_pk_bf16_f32 v240, v115, v119
	v_lshrrev_b32_e32 v241, 2, v240
	v_and_b32_e32 v241, 0x10001, v241
	v_add3_u32 v240, v240, v241, s61
	v_and_b32_e32 v240, 0xfffcfffc, v240
	ds_write_b32 v170, v240 offset:128
	v_cvt_pk_bf16_f32 v238, v116, v120
	v_lshrrev_b32_e32 v239, 2, v238
	v_and_b32_e32 v239, 0x10001, v239
	v_add3_u32 v238, v238, v239, s61
	v_and_b32_e32 v238, 0xfffcfffc, v238
	ds_write_b32 v170, v238 offset:256
	v_cvt_pk_bf16_f32 v240, v117, v121
	v_lshrrev_b32_e32 v241, 2, v240
	v_and_b32_e32 v241, 0x10001, v241
	v_add3_u32 v240, v240, v241, s61
	v_and_b32_e32 v240, 0xfffcfffc, v240
	ds_write_b32 v170, v240 offset:384
	v_cvt_pk_bf16_f32 v238, v122, v126
	v_lshrrev_b32_e32 v239, 2, v238
	v_and_b32_e32 v239, 0x10001, v239
	v_add3_u32 v238, v238, v239, s61
	v_and_b32_e32 v238, 0xfffcfffc, v238
	ds_write_b32 v171, v238
	v_cvt_pk_bf16_f32 v240, v123, v127
	v_lshrrev_b32_e32 v241, 2, v240
	v_and_b32_e32 v241, 0x10001, v241
	v_add3_u32 v240, v240, v241, s61
	v_and_b32_e32 v240, 0xfffcfffc, v240
	ds_write_b32 v171, v240 offset:128
	v_cvt_pk_bf16_f32 v238, v124, v128
	v_lshrrev_b32_e32 v239, 2, v238
	v_and_b32_e32 v239, 0x10001, v239
	v_add3_u32 v238, v238, v239, s61
	v_and_b32_e32 v238, 0xfffcfffc, v238
	ds_write_b32 v171, v238 offset:256
	v_cvt_pk_bf16_f32 v240, v125, v129
	v_lshrrev_b32_e32 v241, 2, v240
	v_and_b32_e32 v241, 0x10001, v241
	v_add3_u32 v240, v240, v241, s61
	v_and_b32_e32 v240, 0xfffcfffc, v240
	ds_write_b32 v171, v240 offset:384
	s_waitcnt lgkmcnt(0)
	ds_read_b128 v[202:205], v182
	ds_read_b128 v[206:209], v183
	ds_read_b128 v[210:213], v184
	ds_read_b128 v[214:217], v185
	s_waitcnt lgkmcnt(3)
	global_store_dwordx4 v190, v[202:205], s[44:45] nt
	s_waitcnt lgkmcnt(2)
	global_store_dwordx4 v191, v[206:209], s[44:45] nt
	s_waitcnt lgkmcnt(1)
	global_store_dwordx4 v192, v[210:213], s[44:45] nt
	s_waitcnt lgkmcnt(0)
	global_store_dwordx4 v193, v[214:217], s[44:45] nt
	ds_read_b128 v[218:221], v186
	ds_read_b128 v[222:225], v187
	ds_read_b128 v[230:233], v188
	ds_read_b128 v[234:237], v189
	s_waitcnt lgkmcnt(3)
	global_store_dwordx4 v194, v[218:221], s[44:45] nt
	s_waitcnt lgkmcnt(2)
	global_store_dwordx4 v195, v[222:225], s[44:45] nt
	s_waitcnt lgkmcnt(1)
	global_store_dwordx4 v196, v[230:233], s[44:45] nt
	s_waitcnt lgkmcnt(0)
	global_store_dwordx4 v197, v[234:237], s[44:45] nt
	s_cmpk_gt_i32 s34, 0x3fff
	s_cbranch_scc0 .Ltpa_loop
.Ltpa_done:
.LBB0_97:
	s_cmpk_gt_i32 s33, 0x1fff
	s_cbranch_scc1 .LBB0_102
	v_mbcnt_lo_u32_b32 v2, -1, 0
	v_mbcnt_hi_u32_b32 v2, -1, v2
	v_and_b32_e32 v3, 64, v2
	v_add_u32_e32 v3, 64, v3
	v_xor_b32_e32 v4, 1, v2
	v_cmp_lt_i32_e32 vcc, v4, v3
	s_ashr_i32 s9, s38, 31
	s_ashr_i32 s10, s67, 31
	v_cndmask_b32_e32 v4, v2, v4, vcc
	v_lshlrev_b32_e32 v72, 2, v4
	v_xor_b32_e32 v4, 2, v2
	v_cmp_lt_i32_e32 vcc, v4, v3
	s_add_u32 s8, s38, s67
	s_load_dwordx2 s[0:1], s[16:17], 0x0
	v_cndmask_b32_e32 v4, v2, v4, vcc
	v_lshlrev_b32_e32 v73, 2, v4
	v_xor_b32_e32 v4, 4, v2
	v_cmp_lt_i32_e32 vcc, v4, v3
	s_addc_u32 s9, s9, s10
	s_lshl_b64 s[10:11], s[8:9], 2
	v_cndmask_b32_e32 v4, v2, v4, vcc
	v_lshlrev_b32_e32 v74, 2, v4
	v_xor_b32_e32 v4, 8, v2
	v_cmp_lt_i32_e32 vcc, v4, v3
	s_add_u32 s24, s10, 0x80000
	s_addc_u32 s25, s11, 0
	v_cndmask_b32_e32 v4, v2, v4, vcc
	v_lshlrev_b32_e32 v75, 2, v4
	v_xor_b32_e32 v4, 16, v2
	v_cmp_lt_i32_e32 vcc, v4, v3
	s_ashr_i32 s73, s72, 31
	s_lshl_b64 s[10:11], s[72:73], 2
	v_cndmask_b32_e32 v4, v2, v4, vcc
	v_lshlrev_b32_e32 v76, 2, v4
	v_xor_b32_e32 v4, 32, v2
	s_lshl_b64 s[16:17], s[8:9], 14
	v_cmp_lt_i32_e32 vcc, v4, v3
	s_waitcnt lgkmcnt(0)
	s_add_u32 s0, s0, s16
	v_lshlrev_b32_e32 v66, 4, v1
	v_cndmask_b32_e32 v2, v2, v4, vcc
	v_mov_b32_e32 v67, 0
	s_addc_u32 s1, s1, s17
	v_lshlrev_b32_e32 v77, 2, v2
	v_lshl_add_u64 v[2:3], s[0:1], 0, v[66:67]
	s_mov_b64 s[0:1], 0x3c00
	v_lshl_add_u64 v[68:69], v[2:3], 0, s[0:1]
	s_lshl_b64 s[0:1], s[8:9], 13
	v_cmp_eq_u32_e64 s[4:5], 0, v1
	s_lshl_b64 s[16:17], s[72:73], 14
	v_lshl_or_b32 v70, v1, 3, s0
	v_mov_b32_e32 v71, s1
	s_lshl_b64 s[18:19], s[72:73], 13
	s_movk_i32 s26, 0xe000
	s_movk_i32 s27, 0xf000
	v_mov_b32_e32 v1, 0x358637bd
	s_mov_b32 s28, 0xf800000
	v_mov_b32_e32 v66, 0x260
	s_mov_b32 s29, 0x1e000000
	s_mov_b32 s30, 0x1e001000
	s_branch .LBB0_100

.LBB0_166:
	s_mov_b64 s[10:11], s[68:69]
	s_load_dwordx2 s[4:5], s[10:11], 0x70
	v_mov_b32_e32 v2, v0
	s_nop 0
	v_readfirstlane_b32 s0, v2
	s_ashr_i32 s36, s0, 6
	s_add_i32 s33, s36, s67
	s_cmpk_gt_i32 s33, 0x3fff
	v_and_b32_e32 v1, 63, v2
	s_cbranch_scc1 .LBB0_189
	s_waitcnt lgkmcnt(0)
	s_add_u32 s37, s4, 0x1000000
	s_addc_u32 s38, s5, 0
	s_add_u32 s39, s4, 0xa000000
	s_addc_u32 s40, s5, 0
	s_lshl_b32 s0, s36, 13
	v_lshlrev_b32_e32 v5, 2, v1
	s_add_i32 s0, s0, 0
	v_and_b32_e32 v3, 15, v2
	v_lshrrev_b32_e32 v4, 4, v1
	v_and_b32_e32 v6, 28, v5
	v_lshlrev_b32_e32 v2, 2, v3
	v_lshl_add_u32 v3, v3, 9, s0
	v_lshlrev_b32_e32 v7, 2, v4
	v_lshlrev_b32_e32 v8, 2, v6
	v_add3_u32 v77, v3, v7, v8
	v_bitop3_b32 v8, v4, v6, 4 bitop3:0x36
	v_bitop3_b32 v9, v4, v6, 8 bitop3:0x36
	v_bitop3_b32 v10, v4, v6, 12 bitop3:0x36
	v_bitop3_b32 v11, v4, v6, 16 bitop3:0x36
	v_bitop3_b32 v12, v4, v6, 20 bitop3:0x36
	v_bitop3_b32 v6, v4, v6, 24 bitop3:0x36
	s_load_dwordx4 s[12:15], s[10:11], 0x8
	s_load_dwordx2 s[16:17], s[10:11], 0x28
	v_lshlrev_b32_e32 v76, 1, v4
	v_or_b32_e32 v7, 4, v4
	v_lshl_add_u32 v78, v8, 2, v3
	v_or_b32_e32 v8, 8, v4
	v_lshl_add_u32 v79, v9, 2, v3
	v_or_b32_e32 v9, 12, v4
	v_lshl_add_u32 v80, v10, 2, v3
	v_or_b32_e32 v10, 16, v4
	v_lshl_add_u32 v81, v11, 2, v3
	v_or_b32_e32 v11, 20, v4
	v_lshl_add_u32 v82, v12, 2, v3
	v_or_b32_e32 v12, 24, v4
	v_lshl_add_u32 v83, v6, 2, v3
	v_or_b32_e32 v6, 28, v4
	v_bitop3_b32 v4, v4, v5, 28 bitop3:0x72
	v_lshrrev_b32_e32 v85, 3, v1
	v_lshl_add_u32 v84, v4, 2, v3
	v_lshlrev_b32_e32 v3, 3, v1
	v_or_b32_e32 v86, 8, v85
	v_or_b32_e32 v87, 16, v85
	v_or_b32_e32 v88, 24, v85
	v_or_b32_e32 v90, 40, v85
	v_or_b32_e32 v91, 48, v85
	v_or_b32_e32 v92, 56, v85
	v_and_b32_e32 v4, 56, v3
	v_lshrrev_b32_e32 v3, 5, v1
	v_lshrrev_b32_e32 v13, 2, v86
	v_lshrrev_b32_e32 v15, 2, v87
	v_lshrrev_b32_e32 v17, 2, v88
	v_lshrrev_b32_e32 v20, 2, v90
	v_lshrrev_b32_e32 v22, 2, v91
	v_lshrrev_b32_e32 v24, 2, v92
	v_xor_b32_e32 v3, v3, v1
	v_xor_b32_e32 v13, v13, v1
	v_xor_b32_e32 v15, v15, v1
	v_xor_b32_e32 v17, v17, v1
	v_xor_b32_e32 v20, v20, v1
	v_xor_b32_e32 v22, v22, v1
	v_xor_b32_e32 v24, v24, v1
	v_lshlrev_b32_e32 v3, 4, v3
	v_lshlrev_b32_e32 v13, 4, v13
	v_lshlrev_b32_e32 v15, 4, v15
	v_lshlrev_b32_e32 v17, 4, v17
	v_or_b32_e32 v89, 32, v85
	v_lshlrev_b32_e32 v20, 4, v20
	v_lshlrev_b32_e32 v22, 4, v22
	v_lshlrev_b32_e32 v24, 4, v24
	s_waitcnt lgkmcnt(0)
	s_cmp_lg_u64 s[12:13], 0
	v_lshl_add_u32 v5, v85, 7, s0
	v_and_b32_e32 v3, 0x70, v3
	v_lshl_add_u32 v14, v86, 7, s0
	v_and_b32_e32 v13, 0x70, v13
	v_lshl_add_u32 v16, v87, 7, s0
	v_and_b32_e32 v15, 0x70, v15
	v_lshl_add_u32 v18, v88, 7, s0
	v_and_b32_e32 v17, 0x70, v17
	v_lshl_add_u32 v19, v89, 7, s0
	v_lshl_add_u32 v21, v90, 7, s0
	v_and_b32_e32 v20, 0x70, v20
	v_lshl_add_u32 v23, v91, 7, s0
	v_and_b32_e32 v22, 0x70, v22
	v_lshl_add_u32 v25, v92, 7, s0
	v_and_b32_e32 v24, 0x70, v24
	s_cselect_b64 s[24:25], -1, 0
	s_lshl_b32 s0, s2, 9
	s_lshl_b32 s1, s36, 6
	s_mov_b32 s19, 0
	v_mov_b32_e32 v67, 0
	v_lshlrev_b32_e32 v93, 1, v7
	v_lshlrev_b32_e32 v94, 1, v8
	v_lshlrev_b32_e32 v95, 1, v9
	v_lshlrev_b32_e32 v96, 1, v10
	v_lshlrev_b32_e32 v97, 1, v11
	v_lshlrev_b32_e32 v98, 1, v12
	v_lshlrev_b32_e32 v99, 1, v6
	s_add_i32 s41, s0, s1
	s_lshl_b32 s42, s3, 9
	s_movk_i32 s43, 0x4000
	s_mov_b32 s44, 0x20000
	s_mov_b32 s45, 0x24000
	s_mov_b32 s46, 0x40000
	s_mov_b32 s47, 0x44000
	s_mov_b32 s48, 0x60000
	s_mov_b32 s49, 0x64000
	s_mov_b32 s50, 0x80000
	s_mov_b32 s51, 0x84000
	s_mov_b32 s53, 0xa0000
	s_mov_b32 s54, 0xa4000
	s_mov_b32 s55, 0xc0000
	s_mov_b32 s56, 0xc4000
	s_mov_b32 s57, 0xe0000
	s_mov_b32 s58, 0xe4000
	s_mov_b32 s59, 0x10001
	v_add_u32_e32 v100, v5, v3
	v_add_u32_e32 v101, v14, v13
	v_add_u32_e32 v102, v16, v15
	v_add_u32_e32 v103, v18, v17
	v_add_u32_e32 v104, v19, v3
	v_add_u32_e32 v105, v21, v20
	v_add_u32_e32 v106, v23, v22
	v_add_u32_e32 v107, v25, v24
	s_mov_b64 s[26:27], 0x4000
	s_mov_b32 s60, 0x8000
	v_lshlrev_b32_e32 v66, 2, v2
	v_lshlrev_b32_e32 v68, 1, v4
	s_load_dwordx2 s[24:25], s[68:69], 0x8
	s_load_dwordx2 s[26:27], s[68:69], 0x10
	s_load_dwordx2 s[28:29], s[68:69], 0x28
	s_load_dwordx2 s[30:31], s[68:69], 0x70
	s_sub_i32 s39, s33, s67
	s_lshl_b32 s39, s39, 13
	s_mov_b32 s61, 0x10001
	v_and_b32_e32 v242, 63, v0
	v_and_b32_e32 v243, 15, v242
	v_lshrrev_b32_e32 v244, 4, v242
	v_and_b32_e32 v245, 7, v242
	v_lshrrev_b32_e32 v246, 3, v242
	v_lshrrev_b32_e32 v247, 5, v242
	v_lshlrev_b32_e32 v248, 4, v243
	v_lshl_add_u32 v198, v244, 16, v248
	v_lshl_add_u32 v199, v244, 15, v248
	v_lshlrev_b32_e32 v200, 3, v244
	v_lshlrev_b32_e32 v248, 9, v243
	v_lshl_add_u32 v248, v244, 2, v248
	v_add_u32_e32 v248, s39, v248
	v_xor_b32_e32 v249, 0, v245
	v_lshl_add_u32 v164, v249, 4, v248
	v_xor_b32_e32 v249, 1, v245
	v_lshl_add_u32 v165, v249, 4, v248
	v_xor_b32_e32 v249, 2, v245
	v_lshl_add_u32 v166, v249, 4, v248
	v_xor_b32_e32 v249, 3, v245
	v_lshl_add_u32 v167, v249, 4, v248
	v_xor_b32_e32 v249, 4, v245
	v_lshl_add_u32 v168, v249, 4, v248
	v_xor_b32_e32 v249, 5, v245
	v_lshl_add_u32 v169, v249, 4, v248
	v_xor_b32_e32 v249, 6, v245
	v_lshl_add_u32 v170, v249, 4, v248
	v_xor_b32_e32 v249, 7, v245
	v_lshl_add_u32 v171, v249, 4, v248
	v_add_u32_e32 v248, 0, v246
	v_add_u32_e32 v249, 0, v247
	v_and_b32_e32 v249, 7, v249
	v_xor_b32_e32 v249, v249, v245
	v_lshlrev_b32_e32 v249, 4, v249
	v_lshl_add_u32 v249, v248, 7, v249
	v_add_u32_e32 v182, s39, v249
	v_lshlrev_b32_e32 v249, 4, v245
	v_lshl_add_u32 v190, v248, 13, v249
	v_add_u32_e32 v248, 8, v246
	v_add_u32_e32 v249, 2, v247
	v_and_b32_e32 v249, 7, v249
	v_xor_b32_e32 v249, v249, v245
	v_lshlrev_b32_e32 v249, 4, v249
	v_lshl_add_u32 v249, v248, 7, v249
	v_add_u32_e32 v183, s39, v249
	v_lshlrev_b32_e32 v249, 4, v245
	v_lshl_add_u32 v191, v248, 13, v249
	v_add_u32_e32 v248, 16, v246
	v_add_u32_e32 v249, 4, v247
	v_and_b32_e32 v249, 7, v249
	v_xor_b32_e32 v249, v249, v245
	v_lshlrev_b32_e32 v249, 4, v249
	v_lshl_add_u32 v249, v248, 7, v249
	v_add_u32_e32 v184, s39, v249
	v_lshlrev_b32_e32 v249, 4, v245
	v_lshl_add_u32 v192, v248, 13, v249
	v_add_u32_e32 v248, 24, v246
	v_add_u32_e32 v249, 6, v247
	v_and_b32_e32 v249, 7, v249
	v_xor_b32_e32 v249, v249, v245
	v_lshlrev_b32_e32 v249, 4, v249
	v_lshl_add_u32 v249, v248, 7, v249
	v_add_u32_e32 v185, s39, v249
	v_lshlrev_b32_e32 v249, 4, v245
	v_lshl_add_u32 v193, v248, 13, v249
	v_add_u32_e32 v248, 32, v246
	v_add_u32_e32 v249, 8, v247
	v_and_b32_e32 v249, 7, v249
	v_xor_b32_e32 v249, v249, v245
	v_lshlrev_b32_e32 v249, 4, v249
	v_lshl_add_u32 v249, v248, 7, v249
	v_add_u32_e32 v186, s39, v249
	v_lshlrev_b32_e32 v249, 4, v245
	v_lshl_add_u32 v194, v248, 13, v249
	v_add_u32_e32 v248, 40, v246
	v_add_u32_e32 v249, 10, v247
	v_and_b32_e32 v249, 7, v249
	v_xor_b32_e32 v249, v249, v245
	v_lshlrev_b32_e32 v249, 4, v249
	v_lshl_add_u32 v249, v248, 7, v249
	v_add_u32_e32 v187, s39, v249
	v_lshlrev_b32_e32 v249, 4, v245
	v_lshl_add_u32 v195, v248, 13, v249
	v_add_u32_e32 v248, 48, v246
	v_add_u32_e32 v249, 12, v247
	v_and_b32_e32 v249, 7, v249
	v_xor_b32_e32 v249, v249, v245
	v_lshlrev_b32_e32 v249, 4, v249
	v_lshl_add_u32 v249, v248, 7, v249
	v_add_u32_e32 v188, s39, v249
	v_lshlrev_b32_e32 v249, 4, v245
	v_lshl_add_u32 v196, v248, 13, v249
	v_add_u32_e32 v248, 56, v246
	v_add_u32_e32 v249, 14, v247
	v_and_b32_e32 v249, 7, v249
	v_xor_b32_e32 v249, v249, v245
	v_lshlrev_b32_e32 v249, 4, v249
	v_lshl_add_u32 v249, v248, 7, v249
	v_add_u32_e32 v189, s39, v249
	v_lshlrev_b32_e32 v249, 4, v245
	v_lshl_add_u32 v197, v248, 13, v249
	s_waitcnt lgkmcnt(0)
	s_mov_b32 s34, s33
	s_cmpk_gt_i32 s34, 0x3fff
	s_cbranch_scc1 .Ltpb_done
	s_cmp_ge_u32 s34, 0x2000
	s_cbranch_scc1 .Ltpb_ldw_p0
	s_lshr_b32 s53, s34, 12
	s_and_b32 s54, s34, 0xfff
	s_lshr_b32 s55, s54, 6
	s_and_b32 s54, s54, 63
	s_lshl_b32 s56, s53, 27
	s_lshl_b32 s57, s55, 21
	s_add_u32 s56, s56, s57
	s_lshl_b32 s57, s54, 8
	s_add_u32 s56, s56, s57
	s_add_u32 s56, s56, 0x4000
	s_add_u32 s48, s26, s56
	s_addc_u32 s49, s27, 0
	s_lshl_b32 s56, s53, 14
	s_lshl_b32 s57, s55, 8
	s_add_u32 s56, s56, s57
	s_add_u32 s50, s24, s56
	s_addc_u32 s51, s25, 0
	s_lshl_b32 s56, s53, 26
	s_lshl_b32 s57, s54, 19
	s_add_u32 s56, s56, s57
	s_lshl_b32 s57, s55, 7
	s_add_u32 s56, s56, s57
	s_add_u32 s56, s56, 0x3000000
	s_add_u32 s40, s30, s56
	s_addc_u32 s41, s31, 0
	s_mov_b32 s42, 1
	s_mov_b32 s43, 24
	global_load_dwordx2 v[132:133], v200, s[50:51] offset:0
	global_load_dwordx2 v[134:135], v200, s[50:51] offset:32
	global_load_dwordx2 v[136:137], v200, s[50:51] offset:64
	global_load_dwordx2 v[138:139], v200, s[50:51] offset:96
	global_load_dwordx2 v[140:141], v200, s[50:51] offset:128
	global_load_dwordx2 v[142:143], v200, s[50:51] offset:160
	global_load_dwordx2 v[144:145], v200, s[50:51] offset:192
	global_load_dwordx2 v[146:147], v200, s[50:51] offset:224
	global_load_dwordx4 v[2:5], v198, s[48:49] nt
	v_add_u32_e32 v6, 0x8000, v198
	global_load_dwordx4 v[6:9], v6, s[48:49] nt
	v_add_u32_e32 v10, 0x40000, v198
	global_load_dwordx4 v[10:13], v10, s[48:49] nt
	v_add_u32_e32 v14, 0x48000, v198
	global_load_dwordx4 v[14:17], v14, s[48:49] nt
	v_add_u32_e32 v18, 0x80000, v198
	global_load_dwordx4 v[18:21], v18, s[48:49] nt
	v_add_u32_e32 v22, 0x88000, v198
	global_load_dwordx4 v[22:25], v22, s[48:49] nt
	v_add_u32_e32 v26, 0xc0000, v198
	global_load_dwordx4 v[26:29], v26, s[48:49] nt
	v_add_u32_e32 v30, 0xc8000, v198
	global_load_dwordx4 v[30:33], v30, s[48:49] nt
	v_add_u32_e32 v34, 0x100000, v198
	global_load_dwordx4 v[34:37], v34, s[48:49] nt
	v_add_u32_e32 v38, 0x108000, v198
	global_load_dwordx4 v[38:41], v38, s[48:49] nt
	v_add_u32_e32 v42, 0x140000, v198
	global_load_dwordx4 v[42:45], v42, s[48:49] nt
	v_add_u32_e32 v46, 0x148000, v198
	global_load_dwordx4 v[46:49], v46, s[48:49] nt
	v_add_u32_e32 v50, 0x180000, v198
	global_load_dwordx4 v[50:53], v50, s[48:49] nt
	v_add_u32_e32 v54, 0x188000, v198
	global_load_dwordx4 v[54:57], v54, s[48:49] nt
	v_add_u32_e32 v58, 0x1c0000, v198
	global_load_dwordx4 v[58:61], v58, s[48:49] nt
	v_add_u32_e32 v62, 0x1c8000, v198
	global_load_dwordx4 v[62:65], v62, s[48:49] nt
	s_branch .Ltpb_ldx_p0

.Ltpb_done:
.LBB0_189:
	s_cmpk_gt_i32 s33, 0x1fff
	s_cbranch_scc1 .LBB0_194
	v_mbcnt_lo_u32_b32 v2, -1, 0
	v_mbcnt_hi_u32_b32 v2, -1, v2
	v_and_b32_e32 v3, 64, v2
	v_add_u32_e32 v3, 64, v3
	v_xor_b32_e32 v4, 1, v2
	v_cmp_lt_i32_e32 vcc, v4, v3
	s_load_dwordx2 s[0:1], s[10:11], 0x0
	s_ashr_i32 s11, s36, 31
	v_cndmask_b32_e32 v4, v2, v4, vcc
	v_lshlrev_b32_e32 v72, 2, v4
	v_xor_b32_e32 v4, 2, v2
	v_cmp_lt_i32_e32 vcc, v4, v3
	s_ashr_i32 s12, s67, 31
	s_add_u32 s10, s36, s67
	v_cndmask_b32_e32 v4, v2, v4, vcc
	v_lshlrev_b32_e32 v73, 2, v4
	v_xor_b32_e32 v4, 4, v2
	v_cmp_lt_i32_e32 vcc, v4, v3
	s_addc_u32 s11, s11, s12
	s_lshl_b64 s[12:13], s[10:11], 2
	v_cndmask_b32_e32 v4, v2, v4, vcc
	v_lshlrev_b32_e32 v74, 2, v4
	v_xor_b32_e32 v4, 8, v2
	v_cmp_lt_i32_e32 vcc, v4, v3
	s_add_u32 s18, s12, 0x80000
	s_addc_u32 s19, s13, 0
	v_cndmask_b32_e32 v4, v2, v4, vcc
	v_lshlrev_b32_e32 v75, 2, v4
	v_xor_b32_e32 v4, 16, v2
	v_cmp_lt_i32_e32 vcc, v4, v3
	s_ashr_i32 s73, s72, 31
	s_lshl_b64 s[12:13], s[72:73], 2
	v_cndmask_b32_e32 v4, v2, v4, vcc
	v_lshlrev_b32_e32 v76, 2, v4
	v_xor_b32_e32 v4, 32, v2
	s_lshl_b64 s[14:15], s[10:11], 14
	v_cmp_lt_i32_e32 vcc, v4, v3
	s_waitcnt lgkmcnt(0)
	s_add_u32 s0, s0, s14
	v_lshlrev_b32_e32 v66, 4, v1
	v_cndmask_b32_e32 v2, v2, v4, vcc
	v_mov_b32_e32 v67, 0
	s_addc_u32 s1, s1, s15
	v_lshlrev_b32_e32 v77, 2, v2
	v_lshl_add_u64 v[2:3], s[0:1], 0, v[66:67]
	s_mov_b64 s[0:1], 0x3c00
	v_lshl_add_u64 v[68:69], v[2:3], 0, s[0:1]
	s_lshl_b64 s[0:1], s[10:11], 13
	v_cmp_eq_u32_e64 s[8:9], 0, v1
	s_lshl_b64 s[14:15], s[72:73], 14
	v_lshl_or_b32 v70, v1, 3, s0
	v_mov_b32_e32 v71, s1
	s_lshl_b64 s[16:17], s[72:73], 13
	s_movk_i32 s24, 0xe000
	s_movk_i32 s25, 0xf000
	v_mov_b32_e32 v1, 0x358637bd
	s_mov_b32 s26, 0xf800000
	v_mov_b32_e32 v66, 0x260
	s_mov_b32 s27, 0x1e000000
	s_mov_b32 s28, 0x1e001000
	s_branch .LBB0_192
